# hgrn pass3: staging loads batched, all q/o_intra/gate/norm-weight loads issued right after the barrier (2 round trips per unit instead of 24)
# baseline (speedup 1.0000x reference)
; #define LAS __attribute__((address_space(3)))
; __device__ __forceinline__ float bflo(unsigned w) { return __uint_as_float(w << 16); }
; __device__ __forceinline__ float bfhi(unsigned w) { return __uint_as_float(w & 0xffff0000u); }
; __device__ __forceinline__ void hgrn_pass3_unit(Frame& F, const float* onw, int pu) {
;     ...
;     for (int i = 0; i < 8; ++i) { const int p = F.tid + 512 * i, cc = p >> 11, q = p & 2047, v = q >> 4, c8 = q & 15;
;         *(LAS v4u*)(F.lds + cc * 34816 + v * 272 + c8 * 16) = *(const v4u*)(UT + (size_t)cc * 16384 + v * 128 + c8 * 8); }
;     __syncthreads();
;     const int cc = F.wave >> 2, tt = F.wave & 3, unit = unit0 + cc, bh = unit >> 7, c = unit & 127, b = bh >> 2, h = bh & 3;
;     const size_t row = (size_t)b * SEQ + c * 64 + 16 * tt + fr;
;     bf16x8_t yq[4];
; #pragma unroll
;     for (int kk = 0; kk < 4; ++kk) yq[kk] = *(const bf16x8_t*)(QO + row * DM + h * 128 + 8 * fq + 32 * kk);
;     f32x4 o[8]; float ss = 0.f;
; #pragma unroll
;     for (int vt = 0; vt < 8; ++vt) { const v2u oi = *(const v2u*)((const bf16*)F.out + (size_t)16 * 1024 * 1024 + row * 512 + h * 128 + 16 * vt + 4 * fq); f32x4 a; a[0] = bflo(oi.x); a[1] = bfhi(oi.x); a[2] = bflo(oi.y); a[3] = bfhi(oi.y);
;     ...
;     for (int vt = 0; vt < 8; ++vt) { const int v0 = 16 * vt + 4 * fq; const f32x4 w4 = *(const f32x4*)(onw + v0); const v2u gt = *(const v2u*)(GH + row * 512 + h * 128 + v0);
.LBB0_696:
	s_ashr_i32 s13, s12, 31
	s_lshl_b64 s[14:15], s[12:13], 15
	s_add_u32 s14, s4, s14
	s_addc_u32 s15, s5, s15
	v_lshl_add_u64 v[110:111], s[14:15], 0, v[44:45]
	v_lshl_add_u64 v[110:111], v[110:111], 0, v[192:193]
	v_mov_b32_e32 v65, v193
	v_lshl_add_u64 v[110:111], v[110:111], 0, v[64:65]
	global_load_dwordx4 v[110:113], v[110:111], off
	v_mov_b32_e32 v67, v193
	v_mov_b32_e32 v69, v193
	v_mov_b32_e32 v71, v193
	v_mov_b32_e32 v73, v193
	v_mov_b32_e32 v75, v193
	v_mov_b32_e32 v77, v193
	s_add_i32 s2, s16, s12
	s_and_b32 s13, s17, 0x1fc0
	v_mov_b32_e32 v79, v193
	v_mov_b32_e32 v81, v193
	s_add_i32 s0, s0, s1
	s_add_i32 s17, s17, s18
	s_add_i32 s12, s12, s19
	v_lshl_add_u64 v[114:115], s[14:15], 0, v[46:47]
	v_lshl_add_u64 v[114:115], v[114:115], 0, v[66:67]
	v_lshl_add_u64 v[114:115], v[114:115], 0, v[64:65]
	global_load_dwordx4 v[114:117], v[114:115], off
	v_lshl_add_u64 v[118:119], s[14:15], 0, v[48:49]
	v_lshl_add_u64 v[118:119], v[118:119], 0, v[68:69]
	v_lshl_add_u64 v[118:119], v[118:119], 0, v[64:65]
	global_load_dwordx4 v[118:121], v[118:119], off
	v_lshl_add_u64 v[122:123], s[14:15], 0, v[50:51]
	v_lshl_add_u64 v[122:123], v[122:123], 0, v[70:71]
	v_lshl_add_u64 v[122:123], v[122:123], 0, v[64:65]
	global_load_dwordx4 v[122:125], v[122:123], off
	v_lshl_add_u64 v[126:127], s[14:15], 0, v[52:53]
	v_lshl_add_u64 v[126:127], v[126:127], 0, v[192:193]
	v_lshl_add_u64 v[126:127], v[126:127], 0, v[64:65]
	global_load_dwordx4 v[126:129], v[126:127], off
	v_lshl_add_u64 v[130:131], s[14:15], 0, v[54:55]
	v_lshl_add_u64 v[130:131], v[130:131], 0, v[72:73]
	v_lshl_add_u64 v[130:131], v[130:131], 0, v[64:65]
	global_load_dwordx4 v[130:133], v[130:131], off
	v_lshl_add_u64 v[134:135], s[14:15], 0, v[56:57]
	v_lshl_add_u64 v[134:135], v[134:135], 0, v[74:75]
	v_lshl_add_u64 v[134:135], v[134:135], 0, v[64:65]
	global_load_dwordx4 v[134:137], v[134:135], off
	v_lshl_add_u64 v[138:139], s[14:15], 0, v[58:59]
	v_lshl_add_u64 v[138:139], v[138:139], 0, v[76:77]
	v_lshl_add_u64 v[138:139], v[138:139], 0, v[64:65]
	global_load_dwordx4 v[138:141], v[138:139], off
	s_ashr_i32 s14, s2, 9
	s_ashr_i32 s15, s14, 31
	s_lshl_b64 s[14:15], s[14:15], 13
	s_or_b32 s13, s14, s13
	s_and_b32 s2, s2, 0x180
	s_lshl_b32 s68, s2, 1
	s_cmpk_gt_i32 s0, 0x1ff
	s_waitcnt vmcnt(7)
	ds_write_b128 v93, v[110:113]
	s_waitcnt vmcnt(6)
	ds_write_b128 v94, v[114:117]
	s_waitcnt vmcnt(5)
	ds_write_b128 v95, v[118:121]
	s_waitcnt vmcnt(4)
	ds_write_b128 v96, v[122:125]
	s_waitcnt vmcnt(3)
	ds_write_b128 v97, v[126:129]
	s_waitcnt vmcnt(2)
	ds_write_b128 v98, v[130:133]
	s_waitcnt vmcnt(1)
	ds_write_b128 v99, v[134:137]
	s_waitcnt vmcnt(0)
	ds_write_b128 v100, v[138:141]
	v_mov_b32_e32 v1, s15
	v_or_b32_e32 v0, s13, v60
	v_lshlrev_b64 v[2:3], 11, v[0:1]
	v_lshlrev_b64 v[84:85], 10, v[0:1]
	v_lshl_add_u64 v[2:3], s[6:7], 0, v[2:3]
	v_lshl_add_u64 v[0:1], s[8:9], 0, v[84:85]
	v_lshl_add_u64 v[82:83], v[2:3], 0, s[68:69]
	v_lshl_add_u64 v[0:1], v[0:1], 0, s[68:69]
	v_lshl_add_u64 v[2:3], v[82:83], 0, v[78:79]
	v_lshl_add_u64 v[86:87], v[0:1], 0, v[80:81]
	s_waitcnt lgkmcnt(0)
	s_barrier
	global_load_dwordx4 v[40:43], v[2:3], off
	global_load_dwordx4 v[36:39], v[2:3], off offset:64
	global_load_dwordx4 v[32:35], v[2:3], off offset:128
	global_load_dwordx4 v[12:15], v[2:3], off offset:192
	global_load_dwordx2 v[144:145], v[86:87], off
	global_load_dwordx2 v[146:147], v[86:87], off offset:32
	global_load_dwordx2 v[148:149], v[86:87], off offset:64
	global_load_dwordx2 v[150:151], v[86:87], off offset:96
	global_load_dwordx2 v[152:153], v[86:87], off offset:128
	global_load_dwordx2 v[154:155], v[86:87], off offset:160
	global_load_dwordx2 v[156:157], v[86:87], off offset:192
	global_load_dwordx2 v[158:159], v[86:87], off offset:224
	v_lshl_add_u64 v[142:143], s[10:11], 0, v[84:85]
	v_lshl_add_u64 v[142:143], v[142:143], 0, s[68:69]
	v_lshl_add_u64 v[142:143], v[142:143], 0, v[80:81]
	global_load_dwordx4 v[160:163], v[62:63], off
	global_load_dwordx4 v[166:169], v[62:63], off offset:64
	global_load_dwordx4 v[172:175], v[62:63], off offset:128
	global_load_dwordx4 v[178:181], v[62:63], off offset:192
	global_load_dwordx4 v[184:187], v[62:63], off offset:256
	global_load_dwordx4 v[204:207], v[62:63], off offset:320
	global_load_dwordx4 v[208:211], v[62:63], off offset:384
	global_load_dwordx4 v[220:223], v[62:63], off offset:448
	global_load_dwordx2 v[164:165], v[142:143], off
	global_load_dwordx2 v[170:171], v[142:143], off offset:32
	global_load_dwordx2 v[176:177], v[142:143], off offset:64
	global_load_dwordx2 v[182:183], v[142:143], off offset:96
	global_load_dwordx2 v[188:189], v[142:143], off offset:128
	global_load_dwordx2 v[190:191], v[142:143], off offset:160
	global_load_dwordx2 v[218:219], v[142:143], off offset:192
	global_load_dwordx2 v[224:225], v[142:143], off offset:224
	s_nop 0
	s_nop 0
	s_nop 0
	s_nop 0
	ds_read_b128 v[4:7], v101
	ds_read_b128 v[102:105], v101 offset:26112
	s_waitcnt vmcnt(23)
	ds_read_b128 v[106:109], v101 offset:30464
	s_waitcnt lgkmcnt(0)
	v_lshlrev_b32_e32 v0, 16, v144
	v_and_b32_e32 v1, 0xffff0000, v144
	v_lshlrev_b32_e32 v2, 16, v145
	v_and_b32_e32 v3, 0xffff0000, v145
	s_nop 1
	v_mfma_f32_16x16x32_bf16 v[0:3], v[4:7], v[40:43], v[0:3]
	ds_read_b128 v[4:7], v101 offset:64
	s_waitcnt lgkmcnt(0)
	v_mfma_f32_16x16x32_bf16 v[0:3], v[4:7], v[36:39], v[0:3]
	ds_read_b128 v[4:7], v101 offset:128
	s_waitcnt lgkmcnt(0)
	v_mfma_f32_16x16x32_bf16 v[0:3], v[4:7], v[32:35], v[0:3]
	ds_read_b128 v[4:7], v101 offset:192
	s_waitcnt lgkmcnt(0)
	v_mfma_f32_16x16x32_bf16 v[28:31], v[4:7], v[12:15], v[0:3]
	s_nop 4
	s_waitcnt vmcnt(22)
; #define LAS __attribute__((address_space(3)))
; __device__ __forceinline__ float bflo(unsigned w) { return __uint_as_float(w << 16); }
; __device__ __forceinline__ float bfhi(unsigned w) { return __uint_as_float(w & 0xffff0000u); }
; __device__ __forceinline__ f32x4 mma16(bf16x8_t x, bf16x8_t y, f32x4 c) { return __builtin_amdgcn_mfma_f32_16x16x32_bf16(x, y, c, 0, 0, 0); }
; __device__ __forceinline__ void hgrn_pass3_unit(Frame& F, const float* onw, int pu) {
;     ...
;     f32x4 o[8]; float ss = 0.f;
; #pragma unroll
;     for (int vt = 0; vt < 8; ++vt) { const v2u oi = *(const v2u*)((const bf16*)F.out + (size_t)16 * 1024 * 1024 + row * 512 + h * 128 + 16 * vt + 4 * fq); f32x4 a; a[0] = bflo(oi.x); a[1] = bfhi(oi.x); a[2] = bflo(oi.y); a[3] = bfhi(oi.y);
; #pragma unroll
;         for (int kk = 0; kk < 4; ++kk) a = mma16(*(const LAS bf16x8_t*)(F.lds + cc * 34816 + (16 * vt + fr) * 272 + (8 * fq + 32 * kk) * 2), yq[kk], a);
;         o[vt] = a; ss += (a[0] * a[0] + a[1] * a[1]) + (a[2] * a[2] + a[3] * a[3]); }
	ds_read_b128 v[4:7], v101 offset:4352
	s_waitcnt lgkmcnt(0)
	v_lshlrev_b32_e32 v0, 16, v146
	v_and_b32_e32 v1, 0xffff0000, v146
	v_lshlrev_b32_e32 v2, 16, v147
	v_and_b32_e32 v3, 0xffff0000, v147
	s_nop 1
	v_mfma_f32_16x16x32_bf16 v[0:3], v[4:7], v[40:43], v[0:3]
	ds_read_b128 v[4:7], v101 offset:4416
	s_waitcnt lgkmcnt(0)
	v_mfma_f32_16x16x32_bf16 v[0:3], v[4:7], v[36:39], v[0:3]
	ds_read_b128 v[4:7], v101 offset:4480
	s_waitcnt lgkmcnt(0)
	v_mfma_f32_16x16x32_bf16 v[0:3], v[4:7], v[32:35], v[0:3]
	ds_read_b128 v[4:7], v101 offset:4544
	s_waitcnt lgkmcnt(0)
	v_mfma_f32_16x16x32_bf16 v[24:27], v[4:7], v[12:15], v[0:3]
	s_nop 4
	v_mov_b32_e32 v2, v29
	v_mov_b32_e32 v0, v28
	v_mov_b32_e32 v4, v31
	v_mov_b32_e32 v3, v25
	v_mov_b32_e32 v1, v24
	v_pk_mul_f32 v[2:3], v[2:3], v[2:3]
	v_mov_b32_e32 v5, v27
	v_pk_fma_f32 v[0:1], v[0:1], v[0:1], v[2:3]
	v_mov_b32_e32 v2, v30
	v_mov_b32_e32 v3, v26
	v_pk_mul_f32 v[4:5], v[4:5], v[4:5]
	s_nop 0
	v_pk_fma_f32 v[2:3], v[2:3], v[2:3], v[4:5]
	ds_read_b128 v[4:7], v101 offset:8704
	v_pk_add_f32 v[88:89], v[0:1], v[2:3]
	s_waitcnt vmcnt(21)
	s_waitcnt lgkmcnt(0)
	v_lshlrev_b32_e32 v0, 16, v148
	v_and_b32_e32 v1, 0xffff0000, v148
	v_lshlrev_b32_e32 v2, 16, v149
	v_and_b32_e32 v3, 0xffff0000, v149
	s_nop 1
	v_mfma_f32_16x16x32_bf16 v[0:3], v[4:7], v[40:43], v[0:3]
	ds_read_b128 v[4:7], v101 offset:8768
	s_waitcnt lgkmcnt(0)
	v_mfma_f32_16x16x32_bf16 v[0:3], v[4:7], v[36:39], v[0:3]
	ds_read_b128 v[4:7], v101 offset:8832
	s_waitcnt lgkmcnt(0)
	v_mfma_f32_16x16x32_bf16 v[0:3], v[4:7], v[32:35], v[0:3]
	ds_read_b128 v[4:7], v101 offset:8896
	s_waitcnt lgkmcnt(0)
	v_mfma_f32_16x16x32_bf16 v[20:23], v[4:7], v[12:15], v[0:3]
	s_nop 7
	v_pk_mul_f32 v[0:1], v[22:23], v[22:23]
	v_pk_mul_f32 v[2:3], v[20:21], v[20:21]
	s_nop 0
	v_pk_mov_b32 v[4:5], v[2:3], v[0:1] op_sel:[1,0]
	v_mov_b32_e32 v3, v1
	v_pk_add_f32 v[90:91], v[4:5], v[2:3]
	s_waitcnt vmcnt(20)
	ds_read_b128 v[4:7], v101 offset:13056
	s_waitcnt lgkmcnt(0)
	v_lshlrev_b32_e32 v0, 16, v150
	v_and_b32_e32 v1, 0xffff0000, v150
	v_lshlrev_b32_e32 v2, 16, v151
	v_and_b32_e32 v3, 0xffff0000, v151
	s_nop 1
	v_mfma_f32_16x16x32_bf16 v[0:3], v[4:7], v[40:43], v[0:3]
	ds_read_b128 v[4:7], v101 offset:13120
	s_waitcnt lgkmcnt(0)
	v_mfma_f32_16x16x32_bf16 v[0:3], v[4:7], v[36:39], v[0:3]
	ds_read_b128 v[4:7], v101 offset:13184
	s_waitcnt lgkmcnt(0)
	v_mfma_f32_16x16x32_bf16 v[0:3], v[4:7], v[32:35], v[0:3]
	ds_read_b128 v[4:7], v101 offset:13248
	s_waitcnt lgkmcnt(0)
	v_mfma_f32_16x16x32_bf16 v[16:19], v[4:7], v[12:15], v[0:3]
	s_nop 4
	s_waitcnt vmcnt(19)
	ds_read_b128 v[4:7], v101 offset:17408
	s_waitcnt lgkmcnt(0)
	v_lshlrev_b32_e32 v0, 16, v152
	v_and_b32_e32 v1, 0xffff0000, v152
	v_lshlrev_b32_e32 v2, 16, v153
	v_and_b32_e32 v3, 0xffff0000, v153
	s_nop 1
	v_mfma_f32_16x16x32_bf16 v[0:3], v[4:7], v[40:43], v[0:3]
	ds_read_b128 v[4:7], v101 offset:17472
	s_waitcnt lgkmcnt(0)
	v_mfma_f32_16x16x32_bf16 v[0:3], v[4:7], v[36:39], v[0:3]
	ds_read_b128 v[4:7], v101 offset:17536
	s_waitcnt lgkmcnt(0)
	v_mfma_f32_16x16x32_bf16 v[0:3], v[4:7], v[32:35], v[0:3]
	ds_read_b128 v[4:7], v101 offset:17600
	s_waitcnt lgkmcnt(0)
	v_mfma_f32_16x16x32_bf16 v[8:11], v[4:7], v[12:15], v[0:3]
	s_nop 4
	v_add_f32_e64 v0, v88, v89
	v_add_f32_e64 v1, v89, v88
	s_nop 0
	v_mul_f32_e32 v2, v8, v8
	v_mul_f32_e32 v4, v9, v9
	v_mov_b32_e32 v1, v2
	v_pk_add_f32 v[2:3], v[90:91], v[90:91] op_sel:[0,1] op_sel_hi:[1,0]
	v_mul_f32_e32 v5, v10, v10
	v_mov_b32_e32 v3, v4
	v_pk_add_f32 v[0:1], v[0:1], v[2:3]
	v_mul_f32_e32 v2, v17, v17
	v_pk_fma_f32 v[2:3], v[16:17], v[16:17], v[2:3] op_sel_hi:[1,1,0]
	v_mul_f32_e32 v4, v19, v19
	v_mul_f32_e32 v6, v11, v11
	v_mov_b32_e32 v3, v5
	v_pk_fma_f32 v[4:5], v[18:19], v[18:19], v[4:5] op_sel_hi:[1,1,0]
	s_nop 0
	v_mov_b32_e32 v5, v6
	v_pk_add_f32 v[2:3], v[2:3], v[4:5]
	ds_read_b128 v[4:7], v101 offset:21760
	v_pk_add_f32 v[88:89], v[0:1], v[2:3]
	s_waitcnt vmcnt(18)
	s_waitcnt lgkmcnt(0)
	v_lshlrev_b32_e32 v0, 16, v154
	v_and_b32_e32 v1, 0xffff0000, v154
	v_lshlrev_b32_e32 v2, 16, v155
	v_and_b32_e32 v3, 0xffff0000, v155
	s_nop 1
	v_mfma_f32_16x16x32_bf16 v[0:3], v[4:7], v[40:43], v[0:3]
	ds_read_b128 v[4:7], v101 offset:21824
	s_waitcnt lgkmcnt(0)
	v_mfma_f32_16x16x32_bf16 v[0:3], v[4:7], v[36:39], v[0:3]
	ds_read_b128 v[4:7], v101 offset:21888
	s_waitcnt lgkmcnt(0)
	v_mfma_f32_16x16x32_bf16 v[0:3], v[4:7], v[32:35], v[0:3]
	ds_read_b128 v[4:7], v101 offset:21952
	s_waitcnt lgkmcnt(0)
	v_mfma_f32_16x16x32_bf16 v[4:7], v[4:7], v[12:15], v[0:3]
	s_nop 7
	v_pk_mul_f32 v[0:1], v[6:7], v[6:7]
	v_pk_mul_f32 v[2:3], v[4:5], v[4:5]
	s_nop 0
	v_pk_mov_b32 v[90:91], v[2:3], v[0:1] op_sel:[1,0]
	v_mov_b32_e32 v3, v1
	v_pk_add_f32 v[90:91], v[90:91], v[2:3]
	s_waitcnt vmcnt(17)
	s_waitcnt lgkmcnt(0)
	v_lshlrev_b32_e32 v0, 16, v156
	s_waitcnt vmcnt(16)
	v_and_b32_e32 v1, 0xffff0000, v156
	v_lshlrev_b32_e32 v2, 16, v157
	v_and_b32_e32 v3, 0xffff0000, v157
	s_nop 1
	v_mfma_f32_16x16x32_bf16 v[0:3], v[102:105], v[40:43], v[0:3]
	ds_read_b128 v[102:105], v101 offset:26176
	s_waitcnt lgkmcnt(0)
	v_mfma_f32_16x16x32_bf16 v[0:3], v[102:105], v[36:39], v[0:3]
	ds_read_b128 v[102:105], v101 offset:26240
	s_waitcnt lgkmcnt(0)
	v_mfma_f32_16x16x32_bf16 v[0:3], v[102:105], v[32:35], v[0:3]
	ds_read_b128 v[102:105], v101 offset:26304
	s_waitcnt lgkmcnt(0)
	v_mfma_f32_16x16x32_bf16 v[0:3], v[102:105], v[12:15], v[0:3]
	s_nop 0
	v_lshlrev_b32_e32 v102, 16, v158
	v_and_b32_e32 v103, 0xffff0000, v158
	v_lshlrev_b32_e32 v104, 16, v159
	v_and_b32_e32 v105, 0xffff0000, v159
	s_nop 1
	v_mfma_f32_16x16x32_bf16 v[40:43], v[106:109], v[40:43], v[102:105]
	s_nop 2
	ds_read_b128 v[102:105], v101 offset:30528
	s_waitcnt lgkmcnt(0)
; __device__ __forceinline__ unsigned cvt_pk_bf16(float lo, float hi) { const f32x2cv v = {lo, hi}; const bf16x2cv b = __builtin_convertvector(v, bf16x2cv); return __builtin_bit_cast(unsigned, b); }
; #define LAS __attribute__((address_space(3)))
; __device__ __forceinline__ float bflo(unsigned w) { return __uint_as_float(w << 16); }
; __device__ __forceinline__ float bfhi(unsigned w) { return __uint_as_float(w & 0xffff0000u); }
; __device__ __forceinline__ f32x4 mma16(bf16x8_t x, bf16x8_t y, f32x4 c) { return __builtin_amdgcn_mfma_f32_16x16x32_bf16(x, y, c, 0, 0, 0); }
; __device__ __forceinline__ void hgrn_pass3_unit(Frame& F, const float* onw, int pu) {
;     ...
;         for (int kk = 0; kk < 4; ++kk) a = mma16(*(const LAS bf16x8_t*)(F.lds + cc * 34816 + (16 * vt + fr) * 272 + (8 * fq + 32 * kk) * 2), yq[kk], a);
;         o[vt] = a; ss += (a[0] * a[0] + a[1] * a[1]) + (a[2] * a[2] + a[3] * a[3]); }
;     ss += __shfl_xor(ss, 16); ss += __shfl_xor(ss, 32);
;     const float rs = __builtin_amdgcn_rsqf(ss * (1.f / 128.f) + EPS);
; #pragma unroll
;     for (int vt = 0; vt < 8; ++vt) { const int v0 = 16 * vt + 4 * fq; const f32x4 w4 = *(const f32x4*)(onw + v0); const v2u gt = *(const v2u*)(GH + row * 512 + h * 128 + v0);
;         v2u w; w.x = cvt_pk_bf16(o[vt][0] * rs * w4[0] * bflo(gt.x), o[vt][1] * rs * w4[1] * bfhi(gt.x)); w.y = cvt_pk_bf16(o[vt][2] * rs * w4[2] * bflo(gt.y), o[vt][3] * rs * w4[3] * bfhi(gt.y));
;         *(v2u*)(QO + row * DM + h * 128 + v0) = w; }
;     __syncthreads();
	v_mfma_f32_16x16x32_bf16 v[36:39], v[102:105], v[36:39], v[40:43]
	s_nop 2
	ds_read_b128 v[40:43], v101 offset:30592
	s_waitcnt lgkmcnt(0)
	v_mfma_f32_16x16x32_bf16 v[32:35], v[40:43], v[32:35], v[36:39]
	s_nop 2
	ds_read_b128 v[36:39], v101 offset:30656
	s_waitcnt lgkmcnt(0)
	v_mfma_f32_16x16x32_bf16 v[12:15], v[36:39], v[12:15], v[32:35]
	s_nop 2
	v_add_f32_e64 v32, v88, v89
	v_add_f32_e64 v33, v89, v88
	s_nop 2
	v_mul_f32_e32 v34, v12, v12
	v_mul_f32_e32 v36, v13, v13
	v_mov_b32_e32 v33, v34
	v_pk_add_f32 v[34:35], v[90:91], v[90:91] op_sel:[0,1] op_sel_hi:[1,0]
	v_mul_f32_e32 v37, v14, v14
	v_mov_b32_e32 v35, v36
	v_pk_add_f32 v[32:33], v[32:33], v[34:35]
	v_mul_f32_e32 v34, v1, v1
	v_pk_fma_f32 v[34:35], v[0:1], v[0:1], v[34:35] op_sel_hi:[1,1,0]
	v_mul_f32_e32 v36, v3, v3
	v_mul_f32_e32 v38, v15, v15
	v_mov_b32_e32 v35, v37
	v_pk_fma_f32 v[36:37], v[2:3], v[2:3], v[36:37] op_sel_hi:[1,1,0]
	s_nop 0
	v_mov_b32_e32 v37, v38
	v_pk_add_f32 v[34:35], v[34:35], v[36:37]
	s_nop 0
	v_pk_add_f32 v[32:33], v[32:33], v[34:35]
	s_nop 0
	s_nop 0
	s_nop 0
	s_waitcnt vmcnt(7)
	v_add_f32_e32 v32, v32, v33
	ds_bpermute_b32 v33, v61, v32
	s_waitcnt lgkmcnt(0)
	v_add_f32_e32 v32, v32, v33
	ds_bpermute_b32 v33, v92, v32
	s_waitcnt lgkmcnt(0)
	v_add_f32_e32 v32, v32, v33
	v_fmamk_f32 v32, v32, 0x3c000000, v212
	v_rsq_f32_e32 v32, v32
	s_nop 0
	v_pk_mul_f32 v[28:29], v[28:29], v[32:33] op_sel_hi:[1,0]
	v_pk_mul_f32 v[24:25], v[24:25], v[32:33] op_sel_hi:[1,0]
	v_pk_mul_f32 v[26:27], v[26:27], v[32:33] op_sel_hi:[1,0]
	v_pk_mul_f32 v[20:21], v[20:21], v[32:33] op_sel_hi:[1,0]
	v_pk_mul_f32 v[22:23], v[22:23], v[32:33] op_sel_hi:[1,0]
	v_pk_mul_f32 v[16:17], v[16:17], v[32:33] op_sel_hi:[1,0]
	v_pk_mul_f32 v[18:19], v[18:19], v[32:33] op_sel_hi:[1,0]
	v_pk_mul_f32 v[8:9], v[8:9], v[32:33] op_sel_hi:[1,0]
	v_pk_mul_f32 v[10:11], v[10:11], v[32:33] op_sel_hi:[1,0]
	v_pk_mul_f32 v[4:5], v[4:5], v[32:33] op_sel_hi:[1,0]
	v_pk_mul_f32 v[6:7], v[6:7], v[32:33] op_sel_hi:[1,0]
	v_pk_mul_f32 v[0:1], v[0:1], v[32:33] op_sel_hi:[1,0]
	v_pk_mul_f32 v[2:3], v[2:3], v[32:33] op_sel_hi:[1,0]
	s_nop 0
	v_pk_mul_f32 v[28:29], v[160:161], v[28:29]
	v_lshlrev_b32_e32 v36, 16, v164
	v_and_b32_e32 v37, 0xffff0000, v164
	v_pk_mul_f32 v[28:29], v[28:29], v[36:37]
	s_nop 0
	v_cvt_pk_bf16_f32 v36, v28, v29
	v_pk_mul_f32 v[28:29], v[30:31], v[32:33] op_sel_hi:[1,0]
	v_lshlrev_b32_e32 v30, 16, v165
	v_pk_mul_f32 v[28:29], v[162:163], v[28:29]
	v_and_b32_e32 v31, 0xffff0000, v165
	v_pk_mul_f32 v[28:29], v[28:29], v[30:31]
	s_nop 0
	v_cvt_pk_bf16_f32 v37, v28, v29
	v_lshl_add_u64 v[28:29], v[82:83], 0, v[80:81]
	global_store_dwordx2 v[28:29], v[36:37], off
	s_nop 0
	s_nop 0
	s_waitcnt vmcnt(7)
	s_nop 0
	v_pk_mul_f32 v[24:25], v[166:167], v[24:25]
	s_waitcnt lgkmcnt(0)
	v_lshlrev_b32_e32 v36, 16, v170
	v_and_b32_e32 v37, 0xffff0000, v170
	v_pk_mul_f32 v[26:27], v[168:169], v[26:27]
	v_lshlrev_b32_e32 v30, 16, v171
	v_and_b32_e32 v31, 0xffff0000, v171
	v_pk_mul_f32 v[24:25], v[24:25], v[36:37]
	v_pk_mul_f32 v[26:27], v[26:27], v[30:31]
	v_cvt_pk_bf16_f32 v24, v24, v25
	v_cvt_pk_bf16_f32 v25, v26, v27
	global_store_dwordx2 v[28:29], v[24:25], off offset:32
	s_nop 0
	s_nop 0
	s_waitcnt vmcnt(7)
	s_nop 0
	v_pk_mul_f32 v[20:21], v[20:21], v[172:173]
	s_waitcnt lgkmcnt(0)
	v_lshlrev_b32_e32 v24, 16, v176
	v_and_b32_e32 v25, 0xffff0000, v176
	v_pk_mul_f32 v[20:21], v[20:21], v[24:25]
	v_pk_mul_f32 v[22:23], v[22:23], v[174:175]
	v_lshlrev_b32_e32 v24, 16, v177
	v_and_b32_e32 v25, 0xffff0000, v177
	v_pk_mul_f32 v[22:23], v[22:23], v[24:25]
	v_cvt_pk_bf16_f32 v20, v20, v21
	v_cvt_pk_bf16_f32 v21, v22, v23
	global_store_dwordx2 v[28:29], v[20:21], off offset:64
	s_nop 0
	s_nop 0
	s_waitcnt vmcnt(7)
	s_nop 0
	v_pk_mul_f32 v[16:17], v[16:17], v[178:179]
	s_waitcnt lgkmcnt(0)
	v_lshlrev_b32_e32 v20, 16, v182
	v_and_b32_e32 v21, 0xffff0000, v182
	v_pk_mul_f32 v[16:17], v[16:17], v[20:21]
	v_pk_mul_f32 v[18:19], v[18:19], v[180:181]
	v_lshlrev_b32_e32 v20, 16, v183
	v_and_b32_e32 v21, 0xffff0000, v183
	v_pk_mul_f32 v[18:19], v[18:19], v[20:21]
	v_cvt_pk_bf16_f32 v16, v16, v17
	v_cvt_pk_bf16_f32 v17, v18, v19
	global_store_dwordx2 v[28:29], v[16:17], off offset:96
	s_nop 0
	s_nop 0
	s_waitcnt vmcnt(7)
	s_nop 0
	v_pk_mul_f32 v[8:9], v[8:9], v[184:185]
	s_waitcnt lgkmcnt(0)
	v_lshlrev_b32_e32 v16, 16, v188
	v_and_b32_e32 v17, 0xffff0000, v188
	v_pk_mul_f32 v[8:9], v[8:9], v[16:17]
	v_pk_mul_f32 v[10:11], v[10:11], v[186:187]
	v_lshlrev_b32_e32 v16, 16, v189
	v_and_b32_e32 v17, 0xffff0000, v189
	v_pk_mul_f32 v[10:11], v[10:11], v[16:17]
	v_cvt_pk_bf16_f32 v8, v8, v9
	v_cvt_pk_bf16_f32 v9, v10, v11
	global_store_dwordx2 v[28:29], v[8:9], off offset:128
	s_nop 0
	s_nop 0
	s_waitcnt vmcnt(7)
	s_nop 0
	v_pk_mul_f32 v[4:5], v[4:5], v[204:205]
	s_waitcnt lgkmcnt(0)
	v_lshlrev_b32_e32 v8, 16, v190
	v_and_b32_e32 v9, 0xffff0000, v190
	v_pk_mul_f32 v[4:5], v[4:5], v[8:9]
	v_pk_mul_f32 v[6:7], v[6:7], v[206:207]
	v_lshlrev_b32_e32 v8, 16, v191
	v_and_b32_e32 v9, 0xffff0000, v191
	v_pk_mul_f32 v[6:7], v[6:7], v[8:9]
	v_cvt_pk_bf16_f32 v4, v4, v5
	v_cvt_pk_bf16_f32 v5, v6, v7
	global_store_dwordx2 v[28:29], v[4:5], off offset:160
	s_nop 0
	s_nop 0
	s_waitcnt vmcnt(7)
	s_nop 0
	v_pk_mul_f32 v[0:1], v[0:1], v[208:209]
	s_waitcnt lgkmcnt(0)
	v_lshlrev_b32_e32 v4, 16, v218
	v_and_b32_e32 v5, 0xffff0000, v218
	v_pk_mul_f32 v[0:1], v[0:1], v[4:5]
	v_pk_mul_f32 v[2:3], v[2:3], v[210:211]
	v_lshlrev_b32_e32 v4, 16, v219
	v_and_b32_e32 v5, 0xffff0000, v219
	v_pk_mul_f32 v[2:3], v[2:3], v[4:5]
	v_cvt_pk_bf16_f32 v0, v0, v1
	v_cvt_pk_bf16_f32 v1, v2, v3
	global_store_dwordx2 v[28:29], v[0:1], off offset:192
	s_nop 0
	s_nop 0
	s_waitcnt vmcnt(7)
	v_pk_mul_f32 v[6:7], v[12:13], v[32:33] op_sel_hi:[1,0]
	s_nop 0
	v_pk_mul_f32 v[0:1], v[6:7], v[220:221]
	s_waitcnt lgkmcnt(0)
	v_lshlrev_b32_e32 v6, 16, v224
	v_and_b32_e32 v7, 0xffff0000, v224
	v_pk_mul_f32 v[0:1], v[0:1], v[6:7]
	v_pk_mul_f32 v[6:7], v[14:15], v[32:33] op_sel_hi:[1,0]
	v_lshlrev_b32_e32 v4, 16, v225
	v_pk_mul_f32 v[2:3], v[6:7], v[222:223]
	v_and_b32_e32 v5, 0xffff0000, v225
	v_pk_mul_f32 v[2:3], v[2:3], v[4:5]
	v_cvt_pk_bf16_f32 v0, v0, v1
	v_cvt_pk_bf16_f32 v1, v2, v3
	global_store_dwordx2 v[28:29], v[0:1], off offset:224
	s_waitcnt lgkmcnt(0)
	s_barrier
	s_cbranch_scc0 .LBB0_696
